# gate/in projection: half-full last round as a 2-way split-K round on all 256 workgroups (K-tiles 0-13 partial via d_ws + per-wave flag, K-tiles 14-31 finisher)
# baseline (speedup 1.0000x reference)
.LBB0_628:
	v_add_u32_e32 v177, 0x10000, v194
	ds_read_b128 v[40:43], v177
	ds_read_b128 v[44:47], v177 offset:1024
	ds_read_b128 v[48:51], v177 offset:2048
	ds_read_b128 v[52:55], v177 offset:3072
	ds_read_b128 v[64:67], v177 offset:16384
	ds_read_b128 v[100:103], v177 offset:17408
	ds_read_b128 v[120:123], v177 offset:18432
	ds_read_b128 v[124:127], v177 offset:19456
	ds_read_b128 v[136:139], v195
	ds_read_b128 v[140:143], v195 offset:1024
	ds_read_b128 v[144:147], v195 offset:2048
	ds_read_b128 v[172:175], v195 offset:3072
	ds_read_b128 v[190:193], v195 offset:4096
	ds_read_b128 v[196:199], v195 offset:5120
	ds_read_b128 v[200:203], v195 offset:6144
	ds_read_b128 v[204:207], v195 offset:7168
	s_add_i32 s39, s3, 1
	s_mul_i32 s4, s39, s60
	s_mul_hi_u32 s5, s39, s0
	s_add_i32 s5, s5, s4
	s_mul_i32 s4, s39, s0
	s_add_u32 s88, s4, s1
	s_addc_u32 s89, s5, s38
	s_cmp_eq_u32 s39, 8
	s_cbranch_scc0 .Lgk_a
	s_cmp_lt_u32 s1, 0x80
	s_cbranch_scc1 .Lgk_a
	s_sub_u32 s88, s88, 0x80
	s_subb_u32 s89, s89, 0
.Lgk_a:
	v_cmp_gt_i64_e32 vcc, s[88:89], v[228:229]
	v_cmp_lt_i64_e64 s[4:5], s[88:89], v[220:221]
	s_cbranch_vccnz .LBB0_630
	s_ashr_i32 s7, s88, 31
	s_lshr_b32 s7, s7, 29
	s_add_i32 s7, s88, s7
	s_ashr_i32 s9, s7, 3
	s_and_b32 s7, s7, -8
	s_sub_i32 s7, s88, s7
	s_cmp_lt_i32 s7, 0
	s_movk_i32 s40, 0x111
	s_cselect_b32 s40, s40, 0x110
	s_mul_i32 s7, s7, s40
	s_add_i32 s7, s7, s9
	s_ashr_i32 s9, s7, 31
	s_lshr_b32 s9, s9, 26
	s_add_i32 s9, s7, s9
	s_ashr_i32 s40, s9, 6
	s_lshl_b32 s40, s40, 2
	s_sub_i32 s41, 0x88, s40
	s_min_i32 s41, s41, 4
	s_abs_i32 s54, s41
	v_cvt_f32_u32_e32 v0, s54
	s_sub_i32 s67, 0, s54
	s_andn2_b32 s9, s9, 63
	s_sub_i32 s7, s7, s9
	v_rcp_iflag_f32_e32 v0, v0
	s_abs_i32 s9, s7
	s_xor_b32 s55, s7, s41
	s_ashr_i32 s55, s55, 31
	v_mul_f32_e32 v0, 0x4f7ffffe, v0
	v_cvt_u32_f32_e32 v0, v0
	s_nop 0
	v_readfirstlane_b32 s84, v0
	s_mul_i32 s67, s67, s84
	s_mul_hi_u32 s67, s84, s67
	s_add_i32 s84, s84, s67
	s_mul_hi_u32 s67, s9, s84
	s_mul_i32 s84, s67, s54
	s_sub_i32 s9, s9, s84
	s_add_i32 s85, s67, 1
	s_sub_i32 s84, s9, s54
	s_cmp_ge_u32 s9, s54
	s_cselect_b32 s67, s85, s67
	s_cselect_b32 s9, s84, s9
	s_add_i32 s84, s67, 1
	s_cmp_ge_u32 s9, s54
	s_cselect_b32 s9, s84, s67
	s_xor_b32 s9, s9, s55
	s_sub_i32 s84, s9, s55
	s_mul_i32 s9, s84, s41
	s_sub_i32 s7, s7, s9
	s_add_i32 s86, s40, s7

.LBB0_638:
	s_ashr_i32 s87, s86, 31
	s_lshl_b64 s[40:41], s[86:87], 20
	s_add_u32 s88, s14, s40
	s_addc_u32 s89, s15, s41
	s_cmp_eq_u32 s39, 8
	s_cbranch_scc0 .Lgk_b1
	s_cmp_lt_u32 s1, 0x80
	s_cbranch_scc1 .Lgk_b1
	s_add_u32 s88, s88, 0x700
	s_addc_u32 s89, s89, 0
.Lgk_b1:
	s_and_b64 s[40:41], s[4:5], exec
	s_cselect_b32 s7, s89, s11
	s_cselect_b32 s9, s88, s10
	s_ashr_i32 s85, s84, 31
	s_lshl_b64 s[40:41], s[84:85], 20
	s_add_u32 s90, s24, s40
	s_addc_u32 s91, s26, s41
	s_cmp_eq_u32 s39, 8
	s_cbranch_scc0 .Lgk_b2
	s_cmp_lt_u32 s1, 0x80
	s_cbranch_scc1 .Lgk_b2
	s_add_u32 s90, s90, 0x700
	s_addc_u32 s91, s91, 0
.Lgk_b2:
	s_and_b64 s[40:41], s[4:5], exec
	s_cselect_b32 s40, s91, s93
	s_cselect_b32 s41, s90, s92
	s_add_u32 s10, s10, 0x80080
	s_addc_u32 s11, s11, 0
	s_add_u32 s54, s92, 0x100
	s_addc_u32 s55, s93, 0
	s_mov_b32 s85, -2
	s_cmp_eq_u32 s39, 9
	s_cbranch_scc0 .Lgk_c
	s_cmp_lt_u32 s1, 0x80
	s_cselect_b32 s85, 16, 12
.Lgk_c:
	s_add_u32 s67, s10, 0xfff80080
	s_addc_u32 s87, s11, -1
	s_add_i32 s96, 0, 0x10000
	s_cmp_eq_u32 s85, 28
	s_cselect_b32 s95, s7, s87
	s_cselect_b32 s94, s9, s67
	s_cselect_b32 s93, s40, s55
	s_cselect_b32 s92, s41, s54
	s_add_i32 s67, 0, 0x14000
	s_add_i32 m0, s57, 0xc000
	global_load_lds_dwordx4 v186, s[10:11]
	s_add_i32 m0, s57, 0xe000
	s_nop 0
	global_load_lds_dwordx4 v188, s[10:11]
	s_waitcnt vmcnt(8)
	s_waitcnt lgkmcnt(0)
	s_barrier
	s_waitcnt lgkmcnt(0)
	v_mfma_f32_16x16x32_bf16 v[168:171], v[40:43], v[136:139], 0
	v_mfma_f32_16x16x32_bf16 v[168:171], v[44:47], v[140:143], v[168:171]
	v_mfma_f32_16x16x32_bf16 v[160:163], v[64:67], v[136:139], 0
	v_mfma_f32_16x16x32_bf16 v[160:163], v[100:103], v[140:143], v[160:163]
	v_mfma_f32_16x16x32_bf16 v[164:167], v[48:51], v[136:139], 0
	v_mfma_f32_16x16x32_bf16 v[164:167], v[52:55], v[140:143], v[164:167]
	v_mfma_f32_16x16x32_bf16 v[132:135], v[64:67], v[144:147], 0
	v_mfma_f32_16x16x32_bf16 v[132:135], v[100:103], v[172:175], v[132:135]
	v_mfma_f32_16x16x32_bf16 v[152:155], v[40:43], v[144:147], 0
	v_mfma_f32_16x16x32_bf16 v[152:155], v[44:47], v[172:175], v[152:155]
	v_mfma_f32_16x16x32_bf16 v[128:131], v[120:123], v[144:147], 0
	v_mfma_f32_16x16x32_bf16 v[128:131], v[124:127], v[172:175], v[128:131]
	v_mfma_f32_16x16x32_bf16 v[148:151], v[48:51], v[144:147], 0
	v_mfma_f32_16x16x32_bf16 v[148:151], v[52:55], v[172:175], v[148:151]
	v_mfma_f32_16x16x32_bf16 v[108:111], v[64:67], v[190:193], 0
	v_mfma_f32_16x16x32_bf16 v[108:111], v[100:103], v[196:199], v[108:111]
	v_mfma_f32_16x16x32_bf16 v[116:119], v[40:43], v[190:193], 0
	v_mfma_f32_16x16x32_bf16 v[116:119], v[44:47], v[196:199], v[116:119]
	v_mfma_f32_16x16x32_bf16 v[104:107], v[120:123], v[190:193], 0
	v_mfma_f32_16x16x32_bf16 v[104:107], v[124:127], v[196:199], v[104:107]
	v_mfma_f32_16x16x32_bf16 v[112:115], v[48:51], v[190:193], 0
	v_mfma_f32_16x16x32_bf16 v[112:115], v[52:55], v[196:199], v[112:115]
	v_mfma_f32_16x16x32_bf16 v[88:91], v[64:67], v[200:203], 0
	v_mfma_f32_16x16x32_bf16 v[88:91], v[100:103], v[204:207], v[88:91]
	v_mfma_f32_16x16x32_bf16 v[96:99], v[40:43], v[200:203], 0
	v_mfma_f32_16x16x32_bf16 v[96:99], v[44:47], v[204:207], v[96:99]
	v_mfma_f32_16x16x32_bf16 v[84:87], v[120:123], v[200:203], 0
	v_mfma_f32_16x16x32_bf16 v[84:87], v[124:127], v[204:207], v[84:87]
	v_mfma_f32_16x16x32_bf16 v[92:95], v[48:51], v[200:203], 0
	v_mfma_f32_16x16x32_bf16 v[92:95], v[52:55], v[204:207], v[92:95]
	v_mfma_f32_16x16x32_bf16 v[136:139], v[120:123], v[136:139], 0
	v_mfma_f32_16x16x32_bf16 v[136:139], v[124:127], v[140:143], v[136:139]
	s_barrier
	s_add_i32 s87, s96, s56
	s_mov_b32 m0, s87
	ds_read_b128 v[140:143], v195 offset:16384
	ds_read_b128 v[144:147], v195 offset:17408
	ds_read_b128 v[156:159], v195 offset:18432
	ds_read_b128 v[172:175], v195 offset:19456
	ds_read_b128 v[190:193], v195 offset:20480
	ds_read_b128 v[196:199], v195 offset:21504
	ds_read_b128 v[200:203], v195 offset:22528
	ds_read_b128 v[204:207], v195 offset:23552
	global_load_lds_dwordx4 v178, s[92:93]
	s_add_i32 m0, s87, 0x2000
	s_add_u32 vcc_lo, s92, 0x80000
	s_addc_u32 vcc_hi, s93, 0
	s_add_i32 s67, s67, s56
	global_load_lds_dwordx4 v182, s[92:93]
	v_lshl_add_u64 v[208:209], vcc, 0, v[178:179]
	s_mov_b32 m0, s67
	s_nop 0
	global_load_lds_dwordx4 v[208:209], off
	v_lshl_add_u64 v[208:209], vcc, 0, v[182:183]
	s_add_i32 m0, s67, 0x2000
	s_nop 0
	global_load_lds_dwordx4 v[208:209], off
	s_mov_b32 m0, s57
	s_nop 0
	global_load_lds_dwordx4 v176, s[94:95]
	s_mov_b32 m0, s61
	s_nop 0
	global_load_lds_dwordx4 v180, s[94:95]
	s_waitcnt vmcnt(8)
	s_waitcnt lgkmcnt(0)
	s_barrier
	s_waitcnt lgkmcnt(0)
	v_mfma_f32_16x16x32_bf16 v[80:83], v[40:43], v[140:143], 0
	v_mfma_f32_16x16x32_bf16 v[80:83], v[44:47], v[144:147], v[80:83]
	v_mfma_f32_16x16x32_bf16 v[36:39], v[64:67], v[156:159], 0
	v_mfma_f32_16x16x32_bf16 v[36:39], v[100:103], v[172:175], v[36:39]
	v_mfma_f32_16x16x32_bf16 v[76:79], v[48:51], v[140:143], 0
	v_mfma_f32_16x16x32_bf16 v[76:79], v[52:55], v[144:147], v[76:79]
	v_mfma_f32_16x16x32_bf16 v[32:35], v[120:123], v[156:159], 0
	v_mfma_f32_16x16x32_bf16 v[32:35], v[124:127], v[172:175], v[32:35]
	v_mfma_f32_16x16x32_bf16 v[60:63], v[40:43], v[156:159], 0
	v_mfma_f32_16x16x32_bf16 v[60:63], v[44:47], v[172:175], v[60:63]
	v_mfma_f32_16x16x32_bf16 v[20:23], v[64:67], v[190:193], 0
	v_mfma_f32_16x16x32_bf16 v[20:23], v[100:103], v[196:199], v[20:23]
	v_mfma_f32_16x16x32_bf16 v[56:59], v[48:51], v[156:159], 0
	v_mfma_f32_16x16x32_bf16 v[56:59], v[52:55], v[172:175], v[56:59]
	v_mfma_f32_16x16x32_bf16 v[16:19], v[120:123], v[190:193], 0
	v_mfma_f32_16x16x32_bf16 v[16:19], v[124:127], v[196:199], v[16:19]
	v_mfma_f32_16x16x32_bf16 v[28:31], v[40:43], v[190:193], 0
	v_mfma_f32_16x16x32_bf16 v[28:31], v[44:47], v[196:199], v[28:31]
	v_mfma_f32_16x16x32_bf16 v[4:7], v[64:67], v[200:203], 0
	v_mfma_f32_16x16x32_bf16 v[4:7], v[100:103], v[204:207], v[4:7]
	v_mfma_f32_16x16x32_bf16 v[24:27], v[48:51], v[190:193], 0
	v_mfma_f32_16x16x32_bf16 v[24:27], v[52:55], v[196:199], v[24:27]
	v_mfma_f32_16x16x32_bf16 v[0:3], v[120:123], v[200:203], 0
	v_mfma_f32_16x16x32_bf16 v[0:3], v[124:127], v[204:207], v[0:3]
	v_mfma_f32_16x16x32_bf16 v[12:15], v[40:43], v[200:203], 0
	v_mfma_f32_16x16x32_bf16 v[12:15], v[44:47], v[204:207], v[12:15]
	v_mfma_f32_16x16x32_bf16 v[40:43], v[64:67], v[140:143], 0
	v_mfma_f32_16x16x32_bf16 v[40:43], v[100:103], v[144:147], v[40:43]
	v_mfma_f32_16x16x32_bf16 v[8:11], v[48:51], v[200:203], 0
	v_mfma_f32_16x16x32_bf16 v[8:11], v[52:55], v[204:207], v[8:11]
	v_mfma_f32_16x16x32_bf16 v[44:47], v[120:123], v[140:143], 0
	v_mfma_f32_16x16x32_bf16 v[44:47], v[124:127], v[144:147], v[44:47]
	s_barrier
	s_add_i32 s67, 0, 0x18000
	s_add_i32 s87, 0, 0x1c000
	ds_read_b128 v[48:51], v177 offset:32768
	ds_read_b128 v[52:55], v177 offset:33792
	ds_read_b128 v[64:67], v177 offset:34816
	ds_read_b128 v[68:71], v177 offset:35840
	ds_read_b128 v[100:103], v177 offset:49152
	ds_read_b128 v[120:123], v177 offset:50176
	ds_read_b128 v[124:127], v177 offset:51200
	ds_read_b128 v[140:143], v177 offset:52224
	s_add_u32 s94, s94, 0x80000
	s_addc_u32 s95, s95, 0
	s_mov_b32 m0, s68
	ds_read_b128 v[72:75], v195 offset:32768
	ds_read_b128 v[144:147], v195 offset:33792
	ds_read_b128 v[172:175], v195 offset:34816
	ds_read_b128 v[190:193], v195 offset:35840
	ds_read_b128 v[196:199], v195 offset:36864
	ds_read_b128 v[200:203], v195 offset:37888
	ds_read_b128 v[204:207], v195 offset:38912
	ds_read_b128 v[208:211], v195 offset:39936
	global_load_lds_dwordx4 v176, s[94:95]
	s_mov_b32 m0, s69
	s_nop 0
	global_load_lds_dwordx4 v180, s[94:95]
	s_waitcnt vmcnt(8)
	s_waitcnt lgkmcnt(0)
	s_barrier
	s_waitcnt lgkmcnt(0)
	v_mfma_f32_16x16x32_bf16 v[156:159], v[48:51], v[72:75], v[168:171]
	v_mfma_f32_16x16x32_bf16 v[168:171], v[52:55], v[144:147], v[156:159]
	v_mfma_f32_16x16x32_bf16 v[156:159], v[64:67], v[72:75], v[164:167]
	v_mfma_f32_16x16x32_bf16 v[164:167], v[68:71], v[144:147], v[156:159]
	v_mfma_f32_16x16x32_bf16 v[152:155], v[48:51], v[172:175], v[152:155]
	v_mfma_f32_16x16x32_bf16 v[152:155], v[52:55], v[190:193], v[152:155]
	v_mfma_f32_16x16x32_bf16 v[148:151], v[64:67], v[172:175], v[148:151]
	v_mfma_f32_16x16x32_bf16 v[148:151], v[68:71], v[190:193], v[148:151]
	v_mfma_f32_16x16x32_bf16 v[116:119], v[48:51], v[196:199], v[116:119]
	v_mfma_f32_16x16x32_bf16 v[116:119], v[52:55], v[200:203], v[116:119]
	v_mfma_f32_16x16x32_bf16 v[112:115], v[64:67], v[196:199], v[112:115]
	v_mfma_f32_16x16x32_bf16 v[112:115], v[68:71], v[200:203], v[112:115]
	v_mfma_f32_16x16x32_bf16 v[96:99], v[48:51], v[204:207], v[96:99]
	v_mfma_f32_16x16x32_bf16 v[96:99], v[52:55], v[208:211], v[96:99]
	v_mfma_f32_16x16x32_bf16 v[92:95], v[64:67], v[204:207], v[92:95]
	v_mfma_f32_16x16x32_bf16 v[92:95], v[68:71], v[208:211], v[92:95]
	v_mfma_f32_16x16x32_bf16 v[156:159], v[100:103], v[72:75], v[160:163]
	v_mfma_f32_16x16x32_bf16 v[160:163], v[120:123], v[144:147], v[156:159]
	v_mfma_f32_16x16x32_bf16 v[72:75], v[124:127], v[72:75], v[136:139]
	v_mfma_f32_16x16x32_bf16 v[156:159], v[140:143], v[144:147], v[72:75]
	v_mfma_f32_16x16x32_bf16 v[72:75], v[100:103], v[172:175], v[132:135]
	v_mfma_f32_16x16x32_bf16 v[132:135], v[120:123], v[190:193], v[72:75]
	v_mfma_f32_16x16x32_bf16 v[72:75], v[124:127], v[172:175], v[128:131]
	v_mfma_f32_16x16x32_bf16 v[128:131], v[140:143], v[190:193], v[72:75]
	v_mfma_f32_16x16x32_bf16 v[72:75], v[100:103], v[196:199], v[108:111]
	v_mfma_f32_16x16x32_bf16 v[108:111], v[120:123], v[200:203], v[72:75]
	v_mfma_f32_16x16x32_bf16 v[72:75], v[124:127], v[196:199], v[104:107]
	v_mfma_f32_16x16x32_bf16 v[104:107], v[140:143], v[200:203], v[72:75]
	v_mfma_f32_16x16x32_bf16 v[72:75], v[100:103], v[204:207], v[88:91]
	v_mfma_f32_16x16x32_bf16 v[88:91], v[120:123], v[208:211], v[72:75]
	v_mfma_f32_16x16x32_bf16 v[72:75], v[124:127], v[204:207], v[84:87]
	v_mfma_f32_16x16x32_bf16 v[84:87], v[140:143], v[208:211], v[72:75]
	s_barrier
	s_add_i32 s67, s67, s56
	s_nop 3
	s_add_u32 s98, s92, 0x80
	s_addc_u32 s99, s93, 0
	s_mov_b32 m0, s67
	ds_read_b128 v[136:139], v195 offset:49152
	ds_read_b128 v[144:147], v195 offset:50176
	ds_read_b128 v[172:175], v195 offset:51200
	ds_read_b128 v[190:193], v195 offset:52224
	ds_read_b128 v[196:199], v195 offset:53248
	ds_read_b128 v[200:203], v195 offset:54272
	ds_read_b128 v[204:207], v195 offset:55296
	ds_read_b128 v[208:211], v195 offset:56320
	global_load_lds_dwordx4 v178, s[98:99]
	s_add_i32 m0, s67, 0x2000
	s_add_u32 s92, s92, 0x80080
	s_addc_u32 s93, s93, 0
	s_add_i32 s67, s87, s56
	global_load_lds_dwordx4 v182, s[98:99]
	s_mov_b32 m0, s67
	s_nop 0
	global_load_lds_dwordx4 v178, s[92:93]
	s_add_i32 m0, s67, 0x2000
	s_nop 0
	global_load_lds_dwordx4 v182, s[92:93]
	s_add_u32 s98, s94, 0xfff80080
	s_addc_u32 s99, s95, -1
	s_mov_b32 m0, s2
	s_nop 0
	global_load_lds_dwordx4 v176, s[98:99]
	s_mov_b32 m0, s28
	s_nop 0
	global_load_lds_dwordx4 v180, s[98:99]
	s_waitcnt vmcnt(8)
	s_waitcnt lgkmcnt(0)
	s_barrier
	s_waitcnt lgkmcnt(0)
	v_mfma_f32_16x16x32_bf16 v[72:75], v[48:51], v[136:139], v[80:83]
	v_mfma_f32_16x16x32_bf16 v[80:83], v[52:55], v[144:147], v[72:75]
	v_mfma_f32_16x16x32_bf16 v[72:75], v[64:67], v[136:139], v[76:79]
	v_mfma_f32_16x16x32_bf16 v[76:79], v[68:71], v[144:147], v[72:75]
	v_mfma_f32_16x16x32_bf16 v[60:63], v[48:51], v[172:175], v[60:63]
	v_mfma_f32_16x16x32_bf16 v[60:63], v[52:55], v[190:193], v[60:63]
	v_mfma_f32_16x16x32_bf16 v[56:59], v[64:67], v[172:175], v[56:59]
	v_mfma_f32_16x16x32_bf16 v[56:59], v[68:71], v[190:193], v[56:59]
	v_mfma_f32_16x16x32_bf16 v[28:31], v[48:51], v[196:199], v[28:31]
	v_mfma_f32_16x16x32_bf16 v[28:31], v[52:55], v[200:203], v[28:31]
	v_mfma_f32_16x16x32_bf16 v[24:27], v[64:67], v[196:199], v[24:27]
	v_mfma_f32_16x16x32_bf16 v[24:27], v[68:71], v[200:203], v[24:27]
	v_mfma_f32_16x16x32_bf16 v[12:15], v[48:51], v[204:207], v[12:15]
	v_mfma_f32_16x16x32_bf16 v[12:15], v[52:55], v[208:211], v[12:15]
	v_mfma_f32_16x16x32_bf16 v[8:11], v[64:67], v[204:207], v[8:11]
	v_mfma_f32_16x16x32_bf16 v[8:11], v[68:71], v[208:211], v[8:11]
	v_mfma_f32_16x16x32_bf16 v[40:43], v[100:103], v[136:139], v[40:43]
	v_mfma_f32_16x16x32_bf16 v[72:75], v[120:123], v[144:147], v[40:43]
	v_mfma_f32_16x16x32_bf16 v[40:43], v[124:127], v[136:139], v[44:47]
	v_mfma_f32_16x16x32_bf16 v[68:71], v[140:143], v[144:147], v[40:43]
	v_mfma_f32_16x16x32_bf16 v[36:39], v[100:103], v[172:175], v[36:39]
	v_mfma_f32_16x16x32_bf16 v[36:39], v[120:123], v[190:193], v[36:39]
	v_mfma_f32_16x16x32_bf16 v[32:35], v[124:127], v[172:175], v[32:35]
	v_mfma_f32_16x16x32_bf16 v[32:35], v[140:143], v[190:193], v[32:35]
	v_mfma_f32_16x16x32_bf16 v[20:23], v[100:103], v[196:199], v[20:23]
	v_mfma_f32_16x16x32_bf16 v[20:23], v[120:123], v[200:203], v[20:23]
	v_mfma_f32_16x16x32_bf16 v[16:19], v[124:127], v[196:199], v[16:19]
	v_mfma_f32_16x16x32_bf16 v[16:19], v[140:143], v[200:203], v[16:19]
	v_mfma_f32_16x16x32_bf16 v[4:7], v[100:103], v[204:207], v[4:7]
	v_mfma_f32_16x16x32_bf16 v[4:7], v[120:123], v[208:211], v[4:7]
	v_mfma_f32_16x16x32_bf16 v[0:3], v[124:127], v[204:207], v[0:3]
	v_mfma_f32_16x16x32_bf16 v[0:3], v[140:143], v[208:211], v[0:3]
	s_barrier
	s_add_i32 s85, s85, 2
	s_add_u32 s10, s10, 0x100
	s_addc_u32 s11, s11, 0
	s_add_u32 s54, s54, 0x100
	s_addc_u32 s55, s55, 0

.LBB0_642:
	s_cmp_eq_u32 s39, 9
	s_cbranch_scc0 .Lgk_epi
	v_readlane_b32 s94, v255, 5
	v_readlane_b32 s95, v255, 22
	v_mbcnt_lo_u32_b32 v208, -1, 0
	v_mbcnt_hi_u32_b32 v208, -1, v208
	v_lshlrev_b32_e32 v208, 4, v208
	v_mov_b32_e32 v209, 0
	s_lshr_b32 s94, s94, 6
	s_and_b32 s40, s1, 0x7f
	s_lshl_b32 s95, s95, 7
	s_add_i32 s95, s95, s40
	s_lshl_b32 s95, s95, 3
	s_add_i32 s95, s95, s94
	s_lshl_b32 s95, s95, 2
	s_add_u32 s98, s14, s95
	s_addc_u32 s99, s15, 0
	s_sub_u32 s98, s98, 0x1757c000
	s_subb_u32 s99, s99, 0
	s_lshl_b32 s40, s40, 3
	s_add_i32 s40, s40, s94
	s_lshl_b32 s40, s40, 15
	s_add_u32 s92, s14, s40
	s_addc_u32 s93, s15, 0
	s_add_u32 s92, s92, 0x19800000
	s_addc_u32 s93, s93, 0
	s_cmp_lt_u32 s1, 0x80
	s_cbranch_scc0 .Lgk_fin
	global_store_dwordx4 v208, v[0:3], s[92:93] sc1
	global_store_dwordx4 v208, v[4:7], s[92:93] offset:1024 sc1
	global_store_dwordx4 v208, v[8:11], s[92:93] offset:2048 sc1
	global_store_dwordx4 v208, v[12:15], s[92:93] offset:3072 sc1
	s_add_u32 s40, s92, 0x1000
	s_addc_u32 s41, s93, 0
	global_store_dwordx4 v208, v[16:19], s[40:41] sc1
	global_store_dwordx4 v208, v[20:23], s[40:41] offset:1024 sc1
	global_store_dwordx4 v208, v[24:27], s[40:41] offset:2048 sc1
	global_store_dwordx4 v208, v[28:31], s[40:41] offset:3072 sc1
	s_add_u32 s40, s92, 0x2000
	s_addc_u32 s41, s93, 0
	global_store_dwordx4 v208, v[32:35], s[40:41] sc1
	global_store_dwordx4 v208, v[36:39], s[40:41] offset:1024 sc1
	global_store_dwordx4 v208, v[56:59], s[40:41] offset:2048 sc1
	global_store_dwordx4 v208, v[60:63], s[40:41] offset:3072 sc1
	s_add_u32 s40, s92, 0x3000
	s_addc_u32 s41, s93, 0
	global_store_dwordx4 v208, v[68:71], s[40:41] sc1
	global_store_dwordx4 v208, v[72:75], s[40:41] offset:1024 sc1
	global_store_dwordx4 v208, v[76:79], s[40:41] offset:2048 sc1
	global_store_dwordx4 v208, v[80:83], s[40:41] offset:3072 sc1
	s_add_u32 s40, s92, 0x4000
	s_addc_u32 s41, s93, 0
	global_store_dwordx4 v208, v[84:87], s[40:41] sc1
	global_store_dwordx4 v208, v[88:91], s[40:41] offset:1024 sc1
	global_store_dwordx4 v208, v[92:95], s[40:41] offset:2048 sc1
	global_store_dwordx4 v208, v[96:99], s[40:41] offset:3072 sc1
	s_add_u32 s40, s92, 0x5000
	s_addc_u32 s41, s93, 0
	global_store_dwordx4 v208, v[104:107], s[40:41] sc1
	global_store_dwordx4 v208, v[108:111], s[40:41] offset:1024 sc1
	global_store_dwordx4 v208, v[112:115], s[40:41] offset:2048 sc1
	global_store_dwordx4 v208, v[116:119], s[40:41] offset:3072 sc1
	s_add_u32 s40, s92, 0x6000
	s_addc_u32 s41, s93, 0
	global_store_dwordx4 v208, v[128:131], s[40:41] sc1
	global_store_dwordx4 v208, v[132:135], s[40:41] offset:1024 sc1
	global_store_dwordx4 v208, v[148:151], s[40:41] offset:2048 sc1
	global_store_dwordx4 v208, v[152:155], s[40:41] offset:3072 sc1
	s_add_u32 s40, s92, 0x7000
	s_addc_u32 s41, s93, 0
	global_store_dwordx4 v208, v[156:159], s[40:41] sc1
	global_store_dwordx4 v208, v[160:163], s[40:41] offset:1024 sc1
	global_store_dwordx4 v208, v[164:167], s[40:41] offset:2048 sc1
	global_store_dwordx4 v208, v[168:171], s[40:41] offset:3072 sc1
	s_waitcnt vmcnt(0)
	v_mov_b32_e32 v210, 1
	s_mov_b64 exec, 1
	global_atomic_add v209, v210, s[98:99]
	s_mov_b64 exec, -1
	s_branch .Lgk_after
.Lgk_fin:
	s_mov_b32 s94, 0
.Lgk_spin:
	global_load_dword v210, v209, s[98:99] sc1
	s_waitcnt vmcnt(0)
	v_readfirstlane_b32 s32, v210
	s_cmp_ge_u32 s32, 1
	s_cbranch_scc1 .Lgk_ready
	s_sleep 2
	s_add_i32 s94, s94, 1
	s_cmp_lt_u32 s94, 0x40000
	s_cbranch_scc1 .Lgk_spin
.Lgk_ready:
	global_load_dwordx4 v[40:43], v208, s[92:93] sc1
	global_load_dwordx4 v[44:47], v208, s[92:93] offset:1024 sc1
	global_load_dwordx4 v[48:51], v208, s[92:93] offset:2048 sc1
	global_load_dwordx4 v[52:55], v208, s[92:93] offset:3072 sc1
	s_add_u32 s40, s92, 0x1000
	s_addc_u32 s41, s93, 0
	global_load_dwordx4 v[64:67], v208, s[40:41] sc1
	global_load_dwordx4 v[100:103], v208, s[40:41] offset:1024 sc1
	global_load_dwordx4 v[120:123], v208, s[40:41] offset:2048 sc1
	global_load_dwordx4 v[124:127], v208, s[40:41] offset:3072 sc1
	s_add_u32 s40, s92, 0x2000
	s_addc_u32 s41, s93, 0
	global_load_dwordx4 v[136:139], v208, s[40:41] sc1
	global_load_dwordx4 v[140:143], v208, s[40:41] offset:1024 sc1
	global_load_dwordx4 v[144:147], v208, s[40:41] offset:2048 sc1
	global_load_dwordx4 v[172:175], v208, s[40:41] offset:3072 sc1
	s_add_u32 s40, s92, 0x3000
	s_addc_u32 s41, s93, 0
	global_load_dwordx4 v[196:199], v208, s[40:41] sc1
	global_load_dwordx4 v[200:203], v208, s[40:41] offset:1024 sc1
	global_load_dwordx4 v[204:207], v208, s[40:41] offset:2048 sc1
	global_load_dwordx4 v[210:213], v208, s[40:41] offset:3072 sc1
	s_waitcnt vmcnt(8)
	v_pk_add_f32 v[0:1], v[0:1], v[40:41]
	v_pk_add_f32 v[2:3], v[2:3], v[42:43]
	v_pk_add_f32 v[4:5], v[4:5], v[44:45]
	v_pk_add_f32 v[6:7], v[6:7], v[46:47]
	v_pk_add_f32 v[8:9], v[8:9], v[48:49]
	v_pk_add_f32 v[10:11], v[10:11], v[50:51]
	v_pk_add_f32 v[12:13], v[12:13], v[52:53]
	v_pk_add_f32 v[14:15], v[14:15], v[54:55]
	v_pk_add_f32 v[16:17], v[16:17], v[64:65]
	v_pk_add_f32 v[18:19], v[18:19], v[66:67]
	v_pk_add_f32 v[20:21], v[20:21], v[100:101]
	v_pk_add_f32 v[22:23], v[22:23], v[102:103]
	v_pk_add_f32 v[24:25], v[24:25], v[120:121]
	v_pk_add_f32 v[26:27], v[26:27], v[122:123]
	v_pk_add_f32 v[28:29], v[28:29], v[124:125]
	v_pk_add_f32 v[30:31], v[30:31], v[126:127]
	s_add_u32 s40, s92, 0x4000
	s_addc_u32 s41, s93, 0
	global_load_dwordx4 v[40:43], v208, s[40:41] sc1
	global_load_dwordx4 v[44:47], v208, s[40:41] offset:1024 sc1
	global_load_dwordx4 v[48:51], v208, s[40:41] offset:2048 sc1
	global_load_dwordx4 v[52:55], v208, s[40:41] offset:3072 sc1
	s_add_u32 s40, s92, 0x5000
	s_addc_u32 s41, s93, 0
	global_load_dwordx4 v[64:67], v208, s[40:41] sc1
	global_load_dwordx4 v[100:103], v208, s[40:41] offset:1024 sc1
	global_load_dwordx4 v[120:123], v208, s[40:41] offset:2048 sc1
	global_load_dwordx4 v[124:127], v208, s[40:41] offset:3072 sc1
	s_waitcnt vmcnt(8)
	v_pk_add_f32 v[32:33], v[32:33], v[136:137]
	v_pk_add_f32 v[34:35], v[34:35], v[138:139]
	v_pk_add_f32 v[36:37], v[36:37], v[140:141]
	v_pk_add_f32 v[38:39], v[38:39], v[142:143]
	v_pk_add_f32 v[56:57], v[56:57], v[144:145]
	v_pk_add_f32 v[58:59], v[58:59], v[146:147]
	v_pk_add_f32 v[60:61], v[60:61], v[172:173]
	v_pk_add_f32 v[62:63], v[62:63], v[174:175]
	v_pk_add_f32 v[68:69], v[68:69], v[196:197]
	v_pk_add_f32 v[70:71], v[70:71], v[198:199]
	v_pk_add_f32 v[72:73], v[72:73], v[200:201]
	v_pk_add_f32 v[74:75], v[74:75], v[202:203]
	v_pk_add_f32 v[76:77], v[76:77], v[204:205]
	v_pk_add_f32 v[78:79], v[78:79], v[206:207]
	v_pk_add_f32 v[80:81], v[80:81], v[210:211]
	v_pk_add_f32 v[82:83], v[82:83], v[212:213]
	s_add_u32 s40, s92, 0x6000
	s_addc_u32 s41, s93, 0
	global_load_dwordx4 v[136:139], v208, s[40:41] sc1
	global_load_dwordx4 v[140:143], v208, s[40:41] offset:1024 sc1
	global_load_dwordx4 v[144:147], v208, s[40:41] offset:2048 sc1
	global_load_dwordx4 v[172:175], v208, s[40:41] offset:3072 sc1
	s_add_u32 s40, s92, 0x7000
	s_addc_u32 s41, s93, 0
	global_load_dwordx4 v[196:199], v208, s[40:41] sc1
	global_load_dwordx4 v[200:203], v208, s[40:41] offset:1024 sc1
	global_load_dwordx4 v[204:207], v208, s[40:41] offset:2048 sc1
	global_load_dwordx4 v[210:213], v208, s[40:41] offset:3072 sc1
	s_waitcnt vmcnt(8)
	v_pk_add_f32 v[84:85], v[84:85], v[40:41]
	v_pk_add_f32 v[86:87], v[86:87], v[42:43]
	v_pk_add_f32 v[88:89], v[88:89], v[44:45]
	v_pk_add_f32 v[90:91], v[90:91], v[46:47]
	v_pk_add_f32 v[92:93], v[92:93], v[48:49]
	v_pk_add_f32 v[94:95], v[94:95], v[50:51]
	v_pk_add_f32 v[96:97], v[96:97], v[52:53]
	v_pk_add_f32 v[98:99], v[98:99], v[54:55]
	v_pk_add_f32 v[104:105], v[104:105], v[64:65]
	v_pk_add_f32 v[106:107], v[106:107], v[66:67]
	v_pk_add_f32 v[108:109], v[108:109], v[100:101]
	v_pk_add_f32 v[110:111], v[110:111], v[102:103]
	v_pk_add_f32 v[112:113], v[112:113], v[120:121]
	v_pk_add_f32 v[114:115], v[114:115], v[122:123]
	v_pk_add_f32 v[116:117], v[116:117], v[124:125]
	v_pk_add_f32 v[118:119], v[118:119], v[126:127]
	s_waitcnt vmcnt(0)
	v_pk_add_f32 v[128:129], v[128:129], v[136:137]
	v_pk_add_f32 v[130:131], v[130:131], v[138:139]
	v_pk_add_f32 v[132:133], v[132:133], v[140:141]
	v_pk_add_f32 v[134:135], v[134:135], v[142:143]
	v_pk_add_f32 v[148:149], v[148:149], v[144:145]
	v_pk_add_f32 v[150:151], v[150:151], v[146:147]
	v_pk_add_f32 v[152:153], v[152:153], v[172:173]
	v_pk_add_f32 v[154:155], v[154:155], v[174:175]
	v_pk_add_f32 v[156:157], v[156:157], v[196:197]
	v_pk_add_f32 v[158:159], v[158:159], v[198:199]
	v_pk_add_f32 v[160:161], v[160:161], v[200:201]
	v_pk_add_f32 v[162:163], v[162:163], v[202:203]
	v_pk_add_f32 v[164:165], v[164:165], v[204:205]
	v_pk_add_f32 v[166:167], v[166:167], v[206:207]
	v_pk_add_f32 v[168:169], v[168:169], v[210:211]
	v_pk_add_f32 v[170:171], v[170:171], v[212:213]

.LBB0_734:
	s_or_b64 exec, exec, s[6:7]
.Lgk_after:
	s_andn2_b64 vcc, exec, s[4:5]
	s_mov_b64 s[4:5], -1
	s_cbranch_vccnz .LBB0_627
.LBB0_735:
	s_andn2_b64 vcc, exec, s[20:21]
	s_cbranch_vccnz .LBB0_626
	s_barrier
	s_branch .LBB0_626
